# c16: dense attention waves cover 64 queries x half of each key tile (K/V fragments from LDS feed two MFMAs), pair-wise partial O/l exchange through LDS at the end
# baseline (speedup 1.0000x reference)
; #define ATA_LOAD(RK, RV, t) do { const size_t tb = (size_t)(t) * 64 * 128; RK[0] = *(const u32x4*)(Kb + tb + goff0); RV[0] = *(const u32x4*)(Vb + tb + goff0); } while (0)
; #define ATA_STORE(RK, RV, st) do { unsigned char* sb_ = smem + (st) * ATA_STAGE; *(u32x4*)(sb_ + ko0) = RK[0]; *(u32x4*)(sb_ + vo0) = RV[0]; } while (0)
; __device__ void attn_a_item(const Params& p, int item, int l, unsigned char* smem) {
;     int tid_ = threadIdx.x; asm volatile("" : "+v"(tid_));
;     const int tid = tid_, lane = tid & 63, w = __builtin_amdgcn_readfirstlane(tid >> 6), r32 = lane & 31, hi = lane >> 5;
;     const int b = item >> 8, r = item & 255, kvh = r >> 7, qblk = (r >> 2) & 31, hq = kvh * 4 + (r & 3);
;     float* lq = (float*)(smem + ATA_LQ) + w * 32;
;     bf16_t* QA = (bf16_t*)(p.ws + WS_QA);
;     const bf16_t* GA = (const bf16_t*)(p.ws + WS_GA);
;     const size_t tokq = (size_t)b * SEQ + qblk * 256 + w * 32;
;     bf16x8 qr[4];
; #pragma unroll
;     for (int ds = 0; ds < 4; ++ds) qr[ds] = *(const bf16x8*)(QA + (tokq + r32) * 512 + hq * 64 + ds * 16 + hi * 8);
;     const bf16_t* Kb = (const bf16_t*)(p.ws + WS_KA) + (size_t)b * SEQ * 128 + kvh * 64;
;     const bf16_t* Vb = (const bf16_t*)(p.ws + WS_VA) + (size_t)b * SEQ * 128 + kvh * 64;
;     const float nshift = -((const float*)(p.ws + WS_BND))[l];
;     f32x16 o0, o1;
; #pragma unroll
;     for (int i = 0; i < 16; ++i) { o0[i] = 0.f; o1[i] = 0.f; }
;     f32x4 la4 = (f32x4){0.f, 0.f, 0.f, 0.f};
;     constexpr int NT = SEQ / 64;
;     const int row0 = tid >> 3, ch0 = tid & 7;
;     const size_t goff0 = (size_t)row0 * 128 + ch0 * 8;
;     const int ko0 = row0 * 144 + ch0 * 16;
;     const int vo0 = 9216 + (ch0 >> 2) * 4096 + row0 * 64 + (ch0 & 3) * 16;
;     u32x4 rkA[1], rvA[1], rkB[1], rvB[1];
;     ...
;     __syncthreads();
;     ATA_LOAD(rkA, rvA, 0); ATA_LOAD(rkB, rvB, 1);
;     ATA_STORE(rkA, rvA, 0);
;     ATA_LOAD(rkA, rvA, 2);
;     __syncthreads();
.LBB0_845:
	v_mov_b32_e32 v11, v210
	v_readfirstlane_b32 s98, v210
	s_bfe_u32 s98, s98, 0x10006
	s_lshl_b32 s99, s98, 15
	s_ashr_i32 s20, s49, 8
	v_readfirstlane_b32 s9, v11
	s_ashr_i32 s17, s9, 1
	s_ashr_i32 s21, s20, 31
	s_lshl_b32 s22, s49, 6
	s_bfe_u32 s12, s49, 0x10007
	s_andn2_b32 s17, s17, 31
	s_lshl_b64 s[18:19], s[20:21], 13
	s_and_b32 s9, s22, 0x1f00
	s_lshl_b32 s24, s12, 7
	s_ashr_i32 s16, s17, 31
	s_or_b32 s9, s18, s9
	s_add_u32 s9, s9, s17
	v_and_b32_e32 v153, 31, v11
	s_addc_u32 s16, s19, s16
	v_or_b32_e32 v0, s9, v153
	v_mov_b32_e32 v1, s16
	s_lshl_b32 s12, s12, 8
	s_and_b32 s18, s22, 0xc0
	v_lshlrev_b64 v[0:1], 10, v[0:1]
	s_or_b32 s18, s12, s18
	v_lshl_add_u64 v[0:1], s[36:37], 0, v[0:1]
	s_lshl_b32 s12, s18, 1
	s_lshl_b64 s[44:45], s[20:21], 21
	v_lshl_add_u64 v[0:1], v[0:1], 0, s[12:13]
	s_add_u32 s12, s11, s44
	s_addc_u32 s19, s46, s45
	v_bfe_u32 v152, v11, 5, 1
	s_add_u32 s20, s47, s44
	v_ashrrev_i32_e32 v8, 3, v11
	v_lshlrev_b32_e32 v80, 4, v152
	s_addc_u32 s21, s48, s45
	v_ashrrev_i32_e32 v9, 31, v8
	v_lshlrev_b32_e32 v23, 4, v11
	v_lshl_add_u64 v[0:1], v[0:1], 0, v[80:81]
	s_add_u32 s20, s20, s24
	v_and_b32_e32 v10, 0x70, v23
	v_lshlrev_b64 v[12:13], 8, v[8:9]
	v_mov_b32_e32 v2, s99
	v_sub_co_u32_e32 v0, vcc, v0, v2
	s_nop 1
	v_subbrev_co_u32_e32 v1, vcc, 0, v1, vcc
	v_add_co_u32_e32 v2, vcc, 0x8000, v0
	s_nop 1
	v_addc_co_u32_e32 v3, vcc, 0, v1, vcc
	global_load_dwordx4 v[82:85], v[0:1], off
	global_load_dwordx4 v[86:89], v[0:1], off offset:32
	global_load_dwordx4 v[90:93], v[0:1], off offset:64
	global_load_dwordx4 v[94:97], v[0:1], off offset:96
	global_load_dwordx4 v[120:123], v[2:3], off
	global_load_dwordx4 v[124:127], v[2:3], off offset:32
	global_load_dwordx4 v[128:131], v[2:3], off offset:64
	global_load_dwordx4 v[132:135], v[2:3], off offset:96
	s_addc_u32 s21, s21, 0
	v_or_b32_e32 v0, v12, v10
	v_mov_b32_e32 v1, v13
	v_lshl_add_u64 v[14:15], s[20:21], 0, v[0:1]
	s_add_u32 s22, s12, s24
	v_add_co_u32_e32 v18, vcc, s34, v14
	s_addc_u32 s23, s19, 0
	s_nop 0
	v_addc_co_u32_e32 v19, vcc, 0, v15, vcc
	s_mov_b32 s19, 0x8000
	global_load_dword v22, v81, s[38:39]
	s_barrier
	v_lshl_add_u64 v[16:17], s[22:23], 0, v[0:1]
	global_load_dwordx4 v[0:3], v[14:15], off
	global_load_dwordx4 v[4:7], v[16:17], off
	v_add_co_u32_e32 v14, vcc, s19, v14
	v_lshlrev_b32_e32 v9, 10, v11
	s_nop 0
	v_addc_co_u32_e32 v15, vcc, 0, v15, vcc
	v_add_co_u32_e32 v20, vcc, s34, v16
	v_and_b32_e32 v9, 0x1000, v9
	s_nop 0
	v_addc_co_u32_e32 v21, vcc, 0, v17, vcc
	v_add_co_u32_e32 v16, vcc, s19, v16
	v_lshlrev_b32_e32 v24, 1, v11
	s_nop 0
	v_addc_co_u32_e32 v17, vcc, 0, v17, vcc
	global_load_dwordx4 v[102:105], v[18:19], off
	global_load_dwordx4 v[110:113], v[20:21], off
	global_load_dwordx4 v[98:101], v[14:15], off
	global_load_dwordx4 v[106:109], v[16:17], off
	v_and_b32_e32 v16, 48, v23
	v_mad_u64_u32 v[14:15], s[20:21], v8, s3, v[10:11]
	v_lshl_or_b32 v8, v8, 6, v16
	v_lshlrev_b32_e32 v25, 3, v11
	v_add_u32_e32 v155, 0, v14
	v_add_u32_e32 v8, v8, v9
	v_and_b32_e32 v18, 32, v24
	v_add_u32_e32 v156, 0, v8
	v_mul_u32_u24_e32 v17, 0x48, v153
	v_lshlrev_b32_e32 v15, 1, v17
	v_mov_b32_e32 v116, 0
	s_mov_b32 s12, 0
	v_and_b32_e32 v154, 63, v11
	v_add3_u32 v80, 0, v15, v80
	s_mul_i32 s99, s98, 0x1200
	v_add_u32_e32 v80, s99, v80
	v_mov_b32_e32 v117, v116
	v_mov_b32_e32 v118, v116
	v_mov_b32_e32 v119, v116
	v_mov_b32_e32 v8, v116
	v_mov_b32_e32 v9, v116
	v_mov_b32_e32 v14, v116
	v_mov_b32_e32 v15, v116
	v_mov_b32_e32 v16, v116
	v_mov_b32_e32 v17, v116
	s_waitcnt vmcnt(5)
	ds_write_b128 v155, v[0:3]
	s_waitcnt vmcnt(4)
	ds_write_b128 v156, v[4:7] offset:9216
	v_and_b32_e32 v0, 24, v25
	v_add3_u32 v2, 0, v18, v0
	v_lshrrev_b32_e32 v0, 3, v11
	v_bfe_u32 v1, v11, 2, 2
	v_and_or_b32 v0, v0, 4, v1
	v_lshlrev_b32_e32 v3, 6, v0
	v_lshl_add_u64 v[0:1], s[44:45], 0, v[12:13]
	v_xor_b32_e32 v32, 0x80000000, v22
	v_or3_b32 v0, v0, s24, v10
	v_mov_b32_e32 v33, v32
	v_mov_b32_e32 v34, v32
	v_mov_b32_e32 v35, v32
	v_mov_b32_e32 v36, v32
	v_mov_b32_e32 v37, v32
	v_mov_b32_e32 v38, v32
	v_mov_b32_e32 v39, v32
	v_mov_b32_e32 v40, v32
	v_mov_b32_e32 v41, v32
	v_mov_b32_e32 v42, v32
	v_mov_b32_e32 v43, v32
	v_mov_b32_e32 v44, v32
	v_mov_b32_e32 v45, v32
	v_mov_b32_e32 v46, v32
	v_mov_b32_e32 v47, v32
	v_lshl_add_u64 v[114:115], s[42:43], 0, v[0:1]
	v_add_u32_e32 v157, v2, v3
	s_lshl_b32 s99, s98, 11
	v_add_u32_e32 v157, s99, v157
	v_mov_b32_e32 v0, v116
	v_mov_b32_e32 v1, v116
	v_mov_b32_e32 v2, v116
	v_mov_b32_e32 v3, v116
	v_mov_b32_e32 v4, v116
	v_mov_b32_e32 v5, v116
	v_mov_b32_e32 v6, v116
	v_mov_b32_e32 v7, v116
	v_mov_b32_e32 v10, v116
	v_mov_b32_e32 v11, v116
	v_mov_b32_e32 v12, v116
	v_mov_b32_e32 v13, v116
	v_mov_b32_e32 v18, v116
	v_mov_b32_e32 v19, v116
	v_mov_b32_e32 v20, v116
	v_mov_b32_e32 v21, v116
	v_mov_b32_e32 v22, v116
	v_mov_b32_e32 v23, v116
	v_mov_b32_e32 v24, v116
	v_mov_b32_e32 v25, v116
	v_mov_b32_e32 v26, v116
	v_mov_b32_e32 v27, v116
	v_mov_b32_e32 v28, v116
	v_mov_b32_e32 v29, v116
	v_mov_b32_e32 v30, v116
	v_mov_b32_e32 v31, v116
	v_mov_b32_e32 v180, 0
	v_mov_b32_e32 v181, 0
	v_mov_b32_e32 v182, 0
	v_mov_b32_e32 v183, 0
	v_mov_b32_e32 v184, 0
	v_mov_b32_e32 v185, 0
	v_mov_b32_e32 v186, 0
	v_mov_b32_e32 v187, 0
	v_mov_b32_e32 v188, 0
	v_mov_b32_e32 v189, 0
	v_mov_b32_e32 v190, 0
	v_mov_b32_e32 v191, 0
	v_mov_b32_e32 v192, 0
	v_mov_b32_e32 v193, 0
	v_mov_b32_e32 v194, 0
	v_mov_b32_e32 v195, 0
	v_mov_b32_e32 v236, 0
	v_mov_b32_e32 v237, 0
	v_mov_b32_e32 v238, 0
	v_mov_b32_e32 v239, 0
	v_mov_b32_e32 v240, 0
	v_mov_b32_e32 v241, 0
	v_mov_b32_e32 v242, 0
	v_mov_b32_e32 v243, 0
	v_mov_b32_e32 v244, 0
	v_mov_b32_e32 v245, 0
	v_mov_b32_e32 v246, 0
	v_mov_b32_e32 v247, 0
	v_mov_b32_e32 v248, 0
	v_mov_b32_e32 v249, 0
	v_mov_b32_e32 v250, 0
	v_mov_b32_e32 v251, 0
	v_mov_b32_e32 v196, 0
	v_mov_b32_e32 v197, 0
	v_mov_b32_e32 v198, 0
	v_mov_b32_e32 v199, 0
	s_waitcnt lgkmcnt(0)
	s_barrier
	s_branch .LBB0_847
; __device__ __forceinline__ void at_qk(f32x16& p0, f32x16& p1, const bf16_t* Ks, const bf16x8* qr, int r32, int hi) {
;     bf16x8 kf[8];
; #pragma unroll
;     for (int ds = 0; ds < 4; ++ds) {
;         kf[2 * ds] = *(const bf16x8*)(Ks + r32 * 72 + ds * 16 + hi * 8);
;         kf[2 * ds + 1] = *(const bf16x8*)(Ks + (r32 + 32) * 72 + ds * 16 + hi * 8);
;     }
;     __builtin_amdgcn_sched_barrier(0);
;     __builtin_amdgcn_s_setprio(1);
; #pragma unroll
;     for (int ds = 0; ds < 4; ++ds) {
;         p0 = __builtin_amdgcn_mfma_f32_32x32x16_bf16(kf[2 * ds], qr[ds], p0, 0, 0, 0);
;         p1 = __builtin_amdgcn_mfma_f32_32x32x16_bf16(kf[2 * ds + 1], qr[ds], p1, 0, 0, 0);
;     }
;     __builtin_amdgcn_s_setprio(0);
;     __builtin_amdgcn_sched_barrier(0);
; }
; __device__ __forceinline__ void at_pv(f32x16& o0, f32x16& o1, const f32x16& p0, const f32x16& p1, const unsigned char* Vs, int lane) {
;     const int hi = lane >> 5;
;     const unsigned char* vb = Vs + ((lane >> 4) & 1) * 32 + (lane & 3) * 8 + (4 * hi + ((lane & 15) >> 2)) * 64;
;     bf16x8 v0[4], v1[4], pa[4];
; #pragma unroll
;     for (int s = 0; s < 4; ++s) {
;         v0[s] = cat8(tr16(vb + s * 1024), tr16(vb + s * 1024 + 512));
;         v1[s] = cat8(tr16(vb + 4096 + s * 1024), tr16(vb + 4096 + s * 1024 + 512));
;     }
; #pragma unroll
;     for (int s = 0; s < 4; ++s) {
;         u32x4 pw;
;         if (s < 2) { pw.x = pk2(p0[8 * s + 0], p0[8 * s + 1]); pw.y = pk2(p0[8 * s + 2], p0[8 * s + 3]); pw.z = pk2(p0[8 * s + 4], p0[8 * s + 5]); pw.w = pk2(p0[8 * s + 6], p0[8 * s + 7]); }
;         else { const int q = s - 2; pw.x = pk2(p1[8 * q + 0], p1[8 * q + 1]); pw.y = pk2(p1[8 * q + 2], p1[8 * q + 3]); pw.z = pk2(p1[8 * q + 4], p1[8 * q + 5]); pw.w = pk2(p1[8 * q + 6], p1[8 * q + 7]); }
;         pa[s] = __builtin_bit_cast(bf16x8, pw);
;     }
; __device__ void attn_a_item(const Params& p, int item, int l, unsigned char* smem) {
;     ...
;     __syncthreads();
;     ATA_LOAD(rkA, rvA, 0); ATA_LOAD(rkB, rvB, 1);
;     ATA_STORE(rkA, rvA, 0);
;     ATA_LOAD(rkA, rvA, 2);
;     __syncthreads();
;     for (int kt = 0; kt < NT; kt += 2) {
;         ATA_COMPUTE(0);
;         ATA_STORE(rkB, rvB, 1);
;         if (kt + 3 < NT) ATA_LOAD(rkB, rvB, kt + 3);
;         __syncthreads();
;         ATA_COMPUTE(1);
;         if (kt + 2 < NT) { ATA_STORE(rkA, rvA, 0); if (kt + 4 < NT) ATA_LOAD(rkA, rvA, kt + 4); }
.LBB0_846:
	s_add_i32 s12, s12, 2
	v_lshl_add_u64 v[114:115], v[114:115], 0, s[14:15]
	s_and_b64 vcc, exec, s[44:45]
	s_waitcnt lgkmcnt(0)
	s_barrier
	s_cbranch_vccnz .LBB0_852
.LBB0_847:
	ds_read_b128 v[136:139], v80
	ds_read_b128 v[140:143], v80 offset:32
	ds_read_b128 v[144:147], v80 offset:64
	ds_read_b128 v[148:151], v80 offset:96
	s_setprio 1
	s_waitcnt lgkmcnt(3)
	v_mfma_f32_32x32x16_bf16 v[48:63], v[136:139], v[82:85], v[32:47]
	v_mfma_f32_32x32x16_bf16 v[64:79], v[136:139], v[120:123], v[32:47]
	s_waitcnt lgkmcnt(2)
	v_mfma_f32_32x32x16_bf16 v[48:63], v[140:143], v[86:89], v[48:63]
	v_mfma_f32_32x32x16_bf16 v[64:79], v[140:143], v[124:127], v[64:79]
	s_waitcnt lgkmcnt(1)
	v_mfma_f32_32x32x16_bf16 v[48:63], v[144:147], v[90:93], v[48:63]
	v_mfma_f32_32x32x16_bf16 v[64:79], v[144:147], v[128:131], v[64:79]
	s_waitcnt lgkmcnt(0)
	v_mfma_f32_32x32x16_bf16 v[48:63], v[148:151], v[94:97], v[48:63]
	v_mfma_f32_32x32x16_bf16 v[64:79], v[148:151], v[132:135], v[64:79]
	s_setprio 0
	ds_read_b64_tr_b16 v[158:159], v157 offset:9216
	ds_read_b64_tr_b16 v[160:161], v157 offset:9728
	ds_read_b64_tr_b16 v[162:163], v157 offset:13312
	ds_read_b64_tr_b16 v[164:165], v157 offset:13824
	ds_read_b64_tr_b16 v[166:167], v157 offset:10240
	ds_read_b64_tr_b16 v[168:169], v157 offset:10752
	ds_read_b64_tr_b16 v[170:171], v157 offset:14336
	ds_read_b64_tr_b16 v[172:173], v157 offset:14848
	s_nop 7
	v_exp_f32_e32 v48, v48
	v_exp_f32_e32 v49, v49
	v_exp_f32_e32 v50, v50
	v_exp_f32_e32 v51, v51
	v_exp_f32_e32 v52, v52
	v_exp_f32_e32 v53, v53
	v_exp_f32_e32 v54, v54
	v_exp_f32_e32 v55, v55
	v_exp_f32_e32 v56, v56
	v_exp_f32_e32 v57, v57
	v_exp_f32_e32 v58, v58
	v_exp_f32_e32 v59, v59
	v_exp_f32_e32 v60, v60
	v_exp_f32_e32 v61, v61
	v_exp_f32_e32 v62, v62
	v_exp_f32_e32 v63, v63
	v_exp_f32_e32 v64, v64
	v_exp_f32_e32 v65, v65
	v_exp_f32_e32 v66, v66
	v_exp_f32_e32 v67, v67
	v_exp_f32_e32 v68, v68
	v_exp_f32_e32 v69, v69
	v_exp_f32_e32 v70, v70
	v_exp_f32_e32 v71, v71
	v_exp_f32_e32 v72, v72
	v_exp_f32_e32 v73, v73
	v_exp_f32_e32 v74, v74
	v_exp_f32_e32 v75, v75
	v_exp_f32_e32 v76, v76
	v_exp_f32_e32 v77, v77
	v_exp_f32_e32 v78, v78
	v_exp_f32_e32 v79, v79
	v_cvt_pk_bf16_f32 v136, v48, v49
	v_cvt_pk_bf16_f32 v137, v50, v51
	v_cvt_pk_bf16_f32 v138, v52, v53
	v_cvt_pk_bf16_f32 v139, v54, v55
	v_cvt_pk_bf16_f32 v140, v56, v57
	v_cvt_pk_bf16_f32 v141, v58, v59
	v_cvt_pk_bf16_f32 v142, v60, v61
	v_cvt_pk_bf16_f32 v143, v62, v63
	v_cvt_pk_bf16_f32 v144, v64, v65
	v_cvt_pk_bf16_f32 v145, v66, v67
	v_cvt_pk_bf16_f32 v146, v68, v69
	v_cvt_pk_bf16_f32 v147, v70, v71
	v_cvt_pk_bf16_f32 v148, v72, v73
	v_cvt_pk_bf16_f32 v149, v74, v75
	v_cvt_pk_bf16_f32 v150, v76, v77
	v_cvt_pk_bf16_f32 v151, v78, v79
	s_setprio 1
	s_waitcnt lgkmcnt(6)
	v_mfma_f32_32x32x16_bf16 v[0:15], v[136:139], v[158:161], v[0:15]
	v_pk_add_f32 v[116:117], v[116:117], v[48:49]
	v_pk_add_f32 v[118:119], v[118:119], v[50:51]
	s_waitcnt lgkmcnt(4)
	v_mfma_f32_32x32x16_bf16 v[16:31], v[136:139], v[162:165], v[16:31]
	v_pk_add_f32 v[116:117], v[116:117], v[52:53]
	v_pk_add_f32 v[118:119], v[118:119], v[54:55]
	v_mfma_f32_32x32x16_bf16 v[180:195], v[144:147], v[158:161], v[180:195]
	v_pk_add_f32 v[116:117], v[116:117], v[56:57]
	v_pk_add_f32 v[118:119], v[118:119], v[58:59]
	v_mfma_f32_32x32x16_bf16 v[236:251], v[144:147], v[162:165], v[236:251]
	v_pk_add_f32 v[116:117], v[116:117], v[60:61]
	v_pk_add_f32 v[118:119], v[118:119], v[62:63]
	s_waitcnt lgkmcnt(2)
	v_mfma_f32_32x32x16_bf16 v[0:15], v[140:143], v[166:169], v[0:15]
	v_pk_add_f32 v[196:197], v[196:197], v[64:65]
	v_pk_add_f32 v[198:199], v[198:199], v[66:67]
	s_waitcnt lgkmcnt(0)
	v_mfma_f32_32x32x16_bf16 v[16:31], v[140:143], v[170:173], v[16:31]
	v_pk_add_f32 v[196:197], v[196:197], v[68:69]
	v_pk_add_f32 v[198:199], v[198:199], v[70:71]
	v_mfma_f32_32x32x16_bf16 v[180:195], v[148:151], v[166:169], v[180:195]
	v_pk_add_f32 v[196:197], v[196:197], v[72:73]
	v_pk_add_f32 v[198:199], v[198:199], v[74:75]
	v_mfma_f32_32x32x16_bf16 v[236:251], v[148:151], v[170:173], v[236:251]
	v_pk_add_f32 v[196:197], v[196:197], v[76:77]
	v_pk_add_f32 v[198:199], v[198:199], v[78:79]
	s_setprio 0
	s_cmpk_lt_u32 s12, 0x7d
	s_waitcnt vmcnt(1)
	ds_write_b128 v155, v[102:105] offset:17408
	s_waitcnt vmcnt(0)
	ds_write_b128 v156, v[110:113] offset:26624
	s_cbranch_scc0 .LBB0_849
	v_add_co_u32_e32 v48, vcc, 0xffbfc000, v114
	s_nop 1
	v_addc_co_u32_e32 v49, vcc, -1, v115, vcc
	v_add_co_u32_e32 v50, vcc, 0xffffc000, v114
	s_nop 1
	v_addc_co_u32_e32 v51, vcc, -1, v115, vcc
	global_load_dwordx4 v[102:105], v[48:49], off
	global_load_dwordx4 v[110:113], v[50:51], off
; __device__ __forceinline__ unsigned pk2(float lo, float hi) { f32x2 v = {lo, hi}; bf16x2_t b = __builtin_convertvector(v, bf16x2_t); return __builtin_bit_cast(unsigned, b); }
; #define ATA_LOAD(RK, RV, t) do { const size_t tb = (size_t)(t) * 64 * 128; RK[0] = *(const u32x4*)(Kb + tb + goff0); RV[0] = *(const u32x4*)(Vb + tb + goff0); } while (0)
; #define ATA_STORE(RK, RV, st) do { unsigned char* sb_ = smem + (st) * ATA_STAGE; *(u32x4*)(sb_ + ko0) = RK[0]; *(u32x4*)(sb_ + vo0) = RV[0]; } while (0)
; __device__ __forceinline__ void at_pv2(f32x16& o0, f32x16& o1, const f32x16& p0, const f32x16& p1, const bf16x8 (&v0)[4], const bf16x8 (&v1)[4]) {
;     bf16x8 pa[4];
; #pragma unroll
;     for (int s = 0; s < 4; ++s) {
;         u32x4 pw;
;         if (s < 2) { pw.x = pk2(p0[8 * s + 0], p0[8 * s + 1]); pw.y = pk2(p0[8 * s + 2], p0[8 * s + 3]); pw.z = pk2(p0[8 * s + 4], p0[8 * s + 5]); pw.w = pk2(p0[8 * s + 6], p0[8 * s + 7]); }
;         else { const int q = s - 2; pw.x = pk2(p1[8 * q + 0], p1[8 * q + 1]); pw.y = pk2(p1[8 * q + 2], p1[8 * q + 3]); pw.z = pk2(p1[8 * q + 4], p1[8 * q + 5]); pw.w = pk2(p1[8 * q + 6], p1[8 * q + 7]); }
;         pa[s] = __builtin_bit_cast(bf16x8, pw);
;     }
;     __builtin_amdgcn_sched_barrier(0);
;     __builtin_amdgcn_s_setprio(1);
; #pragma unroll
;     for (int s = 0; s < 4; ++s) {
;         o0 = __builtin_amdgcn_mfma_f32_32x32x16_bf16(pa[s], v0[s], o0, 0, 0, 0);
;         o1 = __builtin_amdgcn_mfma_f32_32x32x16_bf16(pa[s], v1[s], o1, 0, 0, 0);
;     }
;     __builtin_amdgcn_s_setprio(0);
;     __builtin_amdgcn_sched_barrier(0);
; }
; __device__ void attn_a_item(const Params& p, int item, int l, unsigned char* smem) {
;     ...
;     for (int kt = 0; kt < NT; kt += 2) {
;         ATA_COMPUTE(0);
;         ATA_STORE(rkB, rvB, 1);
;         if (kt + 3 < NT) ATA_LOAD(rkB, rvB, kt + 3);
;         __syncthreads();
;         ATA_COMPUTE(1);
;         if (kt + 2 < NT) { ATA_STORE(rkA, rvA, 0); if (kt + 4 < NT) ATA_LOAD(rkA, rvA, kt + 4); }
;         __syncthreads();
;     }
.LBB0_849:
	s_waitcnt lgkmcnt(0)
	s_barrier
	ds_read_b128 v[136:139], v80 offset:17408
	ds_read_b128 v[140:143], v80 offset:17440
	ds_read_b128 v[144:147], v80 offset:17472
	ds_read_b128 v[148:151], v80 offset:17504
	s_setprio 1
	s_waitcnt lgkmcnt(3)
	v_mfma_f32_32x32x16_bf16 v[48:63], v[136:139], v[82:85], v[32:47]
	v_mfma_f32_32x32x16_bf16 v[64:79], v[136:139], v[120:123], v[32:47]
	s_waitcnt lgkmcnt(2)
	v_mfma_f32_32x32x16_bf16 v[48:63], v[140:143], v[86:89], v[48:63]
	v_mfma_f32_32x32x16_bf16 v[64:79], v[140:143], v[124:127], v[64:79]
	s_waitcnt lgkmcnt(1)
	v_mfma_f32_32x32x16_bf16 v[48:63], v[144:147], v[90:93], v[48:63]
	v_mfma_f32_32x32x16_bf16 v[64:79], v[144:147], v[128:131], v[64:79]
	s_waitcnt lgkmcnt(0)
	v_mfma_f32_32x32x16_bf16 v[48:63], v[148:151], v[94:97], v[48:63]
	v_mfma_f32_32x32x16_bf16 v[64:79], v[148:151], v[132:135], v[64:79]
	s_setprio 0
	ds_read_b64_tr_b16 v[158:159], v157 offset:26624
	ds_read_b64_tr_b16 v[160:161], v157 offset:27136
	ds_read_b64_tr_b16 v[162:163], v157 offset:30720
	ds_read_b64_tr_b16 v[164:165], v157 offset:31232
	ds_read_b64_tr_b16 v[166:167], v157 offset:27648
	ds_read_b64_tr_b16 v[168:169], v157 offset:28160
	ds_read_b64_tr_b16 v[170:171], v157 offset:31744
	ds_read_b64_tr_b16 v[172:173], v157 offset:32256
	s_nop 7
	v_exp_f32_e32 v48, v48
	v_exp_f32_e32 v49, v49
	v_exp_f32_e32 v50, v50
	v_exp_f32_e32 v51, v51
	v_exp_f32_e32 v52, v52
	v_exp_f32_e32 v53, v53
	v_exp_f32_e32 v54, v54
	v_exp_f32_e32 v55, v55
	v_exp_f32_e32 v56, v56
	v_exp_f32_e32 v57, v57
	v_exp_f32_e32 v58, v58
	v_exp_f32_e32 v59, v59
	v_exp_f32_e32 v60, v60
	v_exp_f32_e32 v61, v61
	v_exp_f32_e32 v62, v62
	v_exp_f32_e32 v63, v63
	v_exp_f32_e32 v64, v64
	v_exp_f32_e32 v65, v65
	v_exp_f32_e32 v66, v66
	v_exp_f32_e32 v67, v67
	v_exp_f32_e32 v68, v68
	v_exp_f32_e32 v69, v69
	v_exp_f32_e32 v70, v70
	v_exp_f32_e32 v71, v71
	v_exp_f32_e32 v72, v72
	v_exp_f32_e32 v73, v73
	v_exp_f32_e32 v74, v74
	v_exp_f32_e32 v75, v75
	v_exp_f32_e32 v76, v76
	v_exp_f32_e32 v77, v77
	v_exp_f32_e32 v78, v78
	v_exp_f32_e32 v79, v79
	v_cvt_pk_bf16_f32 v136, v48, v49
	v_cvt_pk_bf16_f32 v137, v50, v51
	v_cvt_pk_bf16_f32 v138, v52, v53
	v_cvt_pk_bf16_f32 v139, v54, v55
	v_cvt_pk_bf16_f32 v140, v56, v57
	v_cvt_pk_bf16_f32 v141, v58, v59
	v_cvt_pk_bf16_f32 v142, v60, v61
	v_cvt_pk_bf16_f32 v143, v62, v63
	v_cvt_pk_bf16_f32 v144, v64, v65
	v_cvt_pk_bf16_f32 v145, v66, v67
	v_cvt_pk_bf16_f32 v146, v68, v69
	v_cvt_pk_bf16_f32 v147, v70, v71
	v_cvt_pk_bf16_f32 v148, v72, v73
	v_cvt_pk_bf16_f32 v149, v74, v75
	v_cvt_pk_bf16_f32 v150, v76, v77
	v_cvt_pk_bf16_f32 v151, v78, v79
	s_setprio 1
	s_waitcnt lgkmcnt(6)
	v_mfma_f32_32x32x16_bf16 v[0:15], v[136:139], v[158:161], v[0:15]
	v_pk_add_f32 v[116:117], v[116:117], v[48:49]
	v_pk_add_f32 v[118:119], v[118:119], v[50:51]
	s_waitcnt lgkmcnt(4)
	v_mfma_f32_32x32x16_bf16 v[16:31], v[136:139], v[162:165], v[16:31]
	v_pk_add_f32 v[116:117], v[116:117], v[52:53]
	v_pk_add_f32 v[118:119], v[118:119], v[54:55]
	v_mfma_f32_32x32x16_bf16 v[180:195], v[144:147], v[158:161], v[180:195]
	v_pk_add_f32 v[116:117], v[116:117], v[56:57]
	v_pk_add_f32 v[118:119], v[118:119], v[58:59]
	v_mfma_f32_32x32x16_bf16 v[236:251], v[144:147], v[162:165], v[236:251]
	v_pk_add_f32 v[116:117], v[116:117], v[60:61]
	v_pk_add_f32 v[118:119], v[118:119], v[62:63]
	s_waitcnt lgkmcnt(2)
	v_mfma_f32_32x32x16_bf16 v[0:15], v[140:143], v[166:169], v[0:15]
	v_pk_add_f32 v[196:197], v[196:197], v[64:65]
	v_pk_add_f32 v[198:199], v[198:199], v[66:67]
	s_waitcnt lgkmcnt(0)
	v_mfma_f32_32x32x16_bf16 v[16:31], v[140:143], v[170:173], v[16:31]
	v_pk_add_f32 v[196:197], v[196:197], v[68:69]
	v_pk_add_f32 v[198:199], v[198:199], v[70:71]
	v_mfma_f32_32x32x16_bf16 v[180:195], v[148:151], v[166:169], v[180:195]
	v_pk_add_f32 v[196:197], v[196:197], v[72:73]
	v_pk_add_f32 v[198:199], v[198:199], v[74:75]
	v_mfma_f32_32x32x16_bf16 v[236:251], v[148:151], v[170:173], v[236:251]
	v_pk_add_f32 v[196:197], v[196:197], v[76:77]
	v_pk_add_f32 v[198:199], v[198:199], v[78:79]
	s_setprio 0
	s_cmpk_gt_u32 s12, 0x7d
	s_cselect_b64 s[44:45], -1, 0
	s_and_b64 vcc, exec, s[44:45]
	s_cbranch_vccnz .LBB0_846
	s_cmpk_gt_u32 s12, 0x7b
	s_waitcnt vmcnt(1)
	ds_write_b128 v155, v[98:101]
	s_waitcnt vmcnt(0)
	ds_write_b128 v156, v[106:109] offset:9216
	s_cbranch_scc1 .LBB0_846
	v_add_co_u32_e32 v98, vcc, 0xffc00000, v114
	s_nop 1
	v_addc_co_u32_e32 v99, vcc, -1, v115, vcc
	global_load_dwordx4 v[98:101], v[98:99], off
	s_nop 0
	global_load_dwordx4 v[106:109], v[114:115], off
	s_branch .LBB0_846
; __device__ __forceinline__ int crow(int r, int hi) { return (r & 3) + 8 * (r >> 2) + 4 * hi; }
; __device__ void attn_a_item(const Params& p, int item, int l, unsigned char* smem) {
;     ...
;     float lacc = (la4.x + la4.y) + (la4.z + la4.w);
;     lacc += __shfl_xor(lacc, 32);
;     if (hi == 0) lq[r32] = lacc;
;     asm volatile("s_waitcnt lgkmcnt(0)" ::: "memory");
; #pragma unroll
;     for (int rr = 0; rr < 16; ++rr) {
;         const int q = crow(rr, hi); const float inv = 1.f / lq[q];
.LBB0_852:
	s_nop 7
	s_nop 7
	v_readfirstlane_b32 s99, v210
	s_lshr_b32 s99, s99, 6
	s_xor_b32 s100, s99, 1
	s_mul_i32 s99, s99, 0x2400
	s_mul_i32 s100, s100, 0x2400
	s_add_i32 s99, s99, 0x9000
	s_add_i32 s100, s100, 0x9000
	v_lshl_add_u32 v204, v154, 4, s99
	v_lshl_add_u32 v205, v154, 4, s100
	s_cmp_lg_u32 s98, 0
	s_cbranch_scc1 .Lq64_send_odd
	ds_write_b128 v204, v[180:183]
	ds_write_b128 v204, v[184:187] offset:1024
	ds_write_b128 v204, v[188:191] offset:2048
	ds_write_b128 v204, v[192:195] offset:3072
	ds_write_b128 v204, v[236:239] offset:4096
	ds_write_b128 v204, v[240:243] offset:5120
	ds_write_b128 v204, v[244:247] offset:6144
	ds_write_b128 v204, v[248:251] offset:7168
	ds_write_b128 v204, v[196:199] offset:8192
	s_branch .Lq64_sent
.Lq64_send_odd:
	ds_write_b128 v204, v[0:3]
	ds_write_b128 v204, v[4:7] offset:1024
	ds_write_b128 v204, v[8:11] offset:2048
	ds_write_b128 v204, v[12:15] offset:3072
	ds_write_b128 v204, v[16:19] offset:4096
	ds_write_b128 v204, v[20:23] offset:5120
	ds_write_b128 v204, v[24:27] offset:6144
	ds_write_b128 v204, v[28:31] offset:7168
	ds_write_b128 v204, v[116:119] offset:8192
.Lq64_sent:
	s_waitcnt lgkmcnt(0)
	s_barrier
	ds_read_b128 v[48:51], v205
	ds_read_b128 v[52:55], v205 offset:1024
	ds_read_b128 v[56:59], v205 offset:2048
	ds_read_b128 v[60:63], v205 offset:3072
	ds_read_b128 v[64:67], v205 offset:4096
	ds_read_b128 v[68:71], v205 offset:5120
	ds_read_b128 v[72:75], v205 offset:6144
	ds_read_b128 v[76:79], v205 offset:7168
	ds_read_b128 v[200:203], v205 offset:8192
	s_waitcnt lgkmcnt(0)
	s_cmp_lg_u32 s98, 0
	s_cbranch_scc1 .Lq64_comb_odd
	v_pk_add_f32 v[0:1], v[0:1], v[48:49]
	v_pk_add_f32 v[2:3], v[2:3], v[50:51]
	v_pk_add_f32 v[4:5], v[4:5], v[52:53]
	v_pk_add_f32 v[6:7], v[6:7], v[54:55]
	v_pk_add_f32 v[8:9], v[8:9], v[56:57]
	v_pk_add_f32 v[10:11], v[10:11], v[58:59]
	v_pk_add_f32 v[12:13], v[12:13], v[60:61]
	v_pk_add_f32 v[14:15], v[14:15], v[62:63]
	v_pk_add_f32 v[16:17], v[16:17], v[64:65]
	v_pk_add_f32 v[18:19], v[18:19], v[66:67]
	v_pk_add_f32 v[20:21], v[20:21], v[68:69]
	v_pk_add_f32 v[22:23], v[22:23], v[70:71]
	v_pk_add_f32 v[24:25], v[24:25], v[72:73]
	v_pk_add_f32 v[26:27], v[26:27], v[74:75]
	v_pk_add_f32 v[28:29], v[28:29], v[76:77]
	v_pk_add_f32 v[30:31], v[30:31], v[78:79]
	v_pk_add_f32 v[116:117], v[116:117], v[200:201]
	v_pk_add_f32 v[118:119], v[118:119], v[202:203]
	s_branch .Lq64_done
.Lq64_comb_odd:
	v_pk_add_f32 v[0:1], v[180:181], v[48:49]
	v_pk_add_f32 v[2:3], v[182:183], v[50:51]
	v_pk_add_f32 v[4:5], v[184:185], v[52:53]
	v_pk_add_f32 v[6:7], v[186:187], v[54:55]
	v_pk_add_f32 v[8:9], v[188:189], v[56:57]
	v_pk_add_f32 v[10:11], v[190:191], v[58:59]
	v_pk_add_f32 v[12:13], v[192:193], v[60:61]
	v_pk_add_f32 v[14:15], v[194:195], v[62:63]
	v_pk_add_f32 v[16:17], v[236:237], v[64:65]
	v_pk_add_f32 v[18:19], v[238:239], v[66:67]
	v_pk_add_f32 v[20:21], v[240:241], v[68:69]
	v_pk_add_f32 v[22:23], v[242:243], v[70:71]
	v_pk_add_f32 v[24:25], v[244:245], v[72:73]
	v_pk_add_f32 v[26:27], v[246:247], v[74:75]
	v_pk_add_f32 v[28:29], v[248:249], v[76:77]
	v_pk_add_f32 v[30:31], v[250:251], v[78:79]
	v_pk_add_f32 v[116:117], v[196:197], v[200:201]
	v_pk_add_f32 v[118:119], v[198:199], v[202:203]
